# P2 queue order: sample cross-attention and sample LRU items taken right after the first 32 items (before the prompt attention items), so the queue tail is made of many equal prompt cross-attention ite
# baseline (speedup 1.0000x reference)
; __device__ __forceinline__ void p2_mixers(CArgs& a0, LAS unsigned char* lds, int tid, int lane, int wid, int rep) {
;     ...
;         __syncthreads();
;         int it_cur = __builtin_amdgcn_readfirstlane((int)*slot);
;         __syncthreads();
;         while (it_cur < P2_PER_XCD) {
;             int it = it_cur;
.LBB0_326:
	s_or_b64 exec, exec, s[6:7]
	s_waitcnt lgkmcnt(0)
	s_barrier
	ds_read_b32 v2, v1
	s_waitcnt lgkmcnt(0)
	s_barrier
	v_readfirstlane_b32 s37, v2
	s_branch .Lq_perm1
.Lq_back1:
	s_cbranch_scc1 .LBB0_319
	s_or_b32 s6, s39, 0xfffff900
	s_and_b32 s7, s82, 3
	v_writelane_b32 v252, s6, 37
	s_lshl_b32 s7, s7, 9
	s_and_b32 s9, s3, 7
	v_writelane_b32 v252, s7, 38
	s_lshl_b32 s8, s12, 8
	s_lshl_b32 s6, s9, 1
	s_lshl_b32 s7, s39, 14
	s_and_b32 s48, s8, 0x300
	s_lshl_b32 s42, s39, 10
	v_writelane_b32 v252, s9, 15
	s_or_b32 s8, s9, 0xfffff900
	s_lshl_b32 s60, s9, 8
	s_mov_b32 s61, s91
	s_lshl_b32 s81, s39, 7
	s_add_i32 s42, s42, 0x20400
	s_lshl_b32 s49, s39, 1
	s_or_b32 s30, s39, 0x1000
	s_or_b32 s96, s39, 0x3000
	v_writelane_b32 v252, s8, 39
	s_or_b32 s34, s6, 0xfff80200
	s_lshl_b32 s6, s7, 1
	v_writelane_b32 v252, s6, 40
	s_branch .LBB0_329

; __device__ __forceinline__ void p2_mixers(CArgs& a0, LAS unsigned char* lds, int tid, int lane, int wid, int rep) {
;     ...
;             if (tid == 0) *slot = nxt;
;             __syncthreads();
;             it_cur = __builtin_amdgcn_readfirstlane((int)*slot);
;             __syncthreads();
.Lq_back2:
	s_cbranch_scc0 .LBB0_318

; #define KARGS() ({ CArgs* p_ = (CArgs*)__builtin_amdgcn_kernarg_segment_ptr(); asm volatile("" : "+s"(p_)); p_; })
; __device__ __forceinline__ void p2_mixers(CArgs& a0, LAS unsigned char* lds, int tid, int lane, int wid, int rep) {
;     ...
;         while (it_cur < P2_PER_XCD) {
;             int it = it_cur;
;             unsigned nxt = 0u;
;             if (tid == 0) nxt = __hip_atomic_fetch_add(queue, 1u, __ATOMIC_RELAXED, __HIP_MEMORY_SCOPE_AGENT);
;             int tid_ = tid; asm volatile("" : "+v"(tid_));
;             P2Ctx C; C.a = KARGS(); unsigned char* ws = C.a->ws; C.lds = lds; C.tid = tid_; C.lane = tid_ & 63; C.wid = __builtin_amdgcn_readfirstlane(tid_ >> 6);
;             C.Q = (const bf16_t*)(ws + WS_Q); C.Kb = (const bf16_t*)(ws + WS_K); C.Vb = (const bf16_t*)(ws + WS_V); C.XB = (const bf16_t*)(ws + WS_XB); C.GG = (const bf16_t*)(ws + WS_GG);
;             C.QC = (const bf16_t*)(ws + WS_QC); C.MK = (const bf16_t*)(ws + WS_MK); C.MV = (const bf16_t*)(ws + WS_MV); C.WRG = (const bf16_t*)(ws + WS_WRG);
;             C.AO = (bf16_t*)(ws + WS_AO); C.BO = (bf16_t*)(ws + WS_BO); C.CO = (bf16_t*)(ws + WS_CO); C.pf = 0;
;     ...
;             if (rep) { C.pf = PROBE_FLAGS; if (PROBE_FLAGS) { C.AO = C.BO = C.CO = (bf16_t*)(ws + WS_MG); } }
;             if (it < 16) { if (umask & 1) lru_unit_p(C, it >> 1, qx, it & 1); }
;             else if ((it -= 16) < 16) { if (umask & 2) attnB_unit(C, it, qx); }
;             else if ((it -= 16) < 128) { if (umask & 4) attnA_unit(C, it & 7, qx, 15 - (it >> 3)); }
;             else if ((it -= 128) < 64) { const int bh = (it >> 4) * 8 + qx; if (umask & 8) attnC_dma(C, bh >> 2, bh & 3, it & 15); }
;             else if ((it -= 64) < 8) { const int bh = it * 8 + qx; if (umask & 16) attnC_unit<true>(C, bh >> 2, bh & 3, 0); }
;             else { it -= 8; const int idx = it * 8 + qx; if (umask & 32) lru_unit(C, 8 + (idx >> 3), idx & 7); }
.Lq_perm1:
	s_sub_u32 s98, s37, 32
	s_cmp_lt_u32 s98, 0xd8
	s_cbranch_scc0 .Lq_p1d
	s_cmp_lt_u32 s98, 24
	s_cselect_b32 s98, 0xd8, 0
	s_add_i32 s37, s37, s98
	s_sub_i32 s37, s37, 24
.Lq_p1d:
	s_cmpk_gt_i32 s37, 0xf7
	s_branch .Lq_back1

; __device__ __forceinline__ void p2_mixers(CArgs& a0, LAS unsigned char* lds, int tid, int lane, int wid, int rep) {
;     ...
;             it_cur = __builtin_amdgcn_readfirstlane((int)*slot);
;             __syncthreads();
.Lq_p2d:
	s_cmpk_lt_i32 s37, 0xf8
	s_branch .Lq_back2

; __global__ void __launch_bounds__(NWAVES * 64, 2) fwd_kernel(Args args) {
;     __shared__ __attribute__((aligned(16))) unsigned char lds_raw[LDS_BYTES];
	.amdhsa_kernel _Z10fwd_kernel4Args
		.amdhsa_group_segment_fixed_size 147456
		.amdhsa_private_segment_fixed_size 0
		.amdhsa_kernarg_size 576
		.amdhsa_user_sgpr_count 2
		.amdhsa_user_sgpr_dispatch_ptr 0
		.amdhsa_user_sgpr_queue_ptr 0
		.amdhsa_user_sgpr_kernarg_segment_ptr 1
		.amdhsa_user_sgpr_dispatch_id 0
		.amdhsa_user_sgpr_kernarg_preload_length 0
		.amdhsa_user_sgpr_kernarg_preload_offset 0
		.amdhsa_user_sgpr_private_segment_size 0
		.amdhsa_uses_dynamic_stack 0
		.amdhsa_enable_private_segment 0
		.amdhsa_system_sgpr_workgroup_id_x 1
		.amdhsa_system_sgpr_workgroup_id_y 0
		.amdhsa_system_sgpr_workgroup_id_z 0
		.amdhsa_system_sgpr_workgroup_info 0
		.amdhsa_system_vgpr_workitem_id 0
		.amdhsa_next_free_vgpr 253
		.amdhsa_next_free_sgpr 102
		.amdhsa_accum_offset 256
		.amdhsa_reserve_vcc 1
		.amdhsa_float_round_mode_32 0
		.amdhsa_float_round_mode_16_64 0
		.amdhsa_float_denorm_mode_32 3
		.amdhsa_float_denorm_mode_16_64 3
		.amdhsa_dx10_clamp 1
		.amdhsa_ieee_mode 1
		.amdhsa_fp16_overflow 0
		.amdhsa_tg_split 0
		.amdhsa_exception_fp_ieee_invalid_op 0
		.amdhsa_exception_fp_denorm_src 0
		.amdhsa_exception_fp_ieee_div_zero 0
		.amdhsa_exception_fp_ieee_overflow 0
		.amdhsa_exception_fp_ieee_underflow 0
		.amdhsa_exception_fp_ieee_inexact 0
		.amdhsa_exception_int_div_zero 0
	.end_amdhsa_kernel

; __global__ void __launch_bounds__(NWAVES * 64, 2) fwd_kernel(Args args) {
.Lfunc_end0:
	.size	_Z10fwd_kernel4Args, .Lfunc_end0-_Z10fwd_kernel4Args
	.set _Z10fwd_kernel4Args.num_vgpr, 253
	.set _Z10fwd_kernel4Args.num_agpr, 0
	.set _Z10fwd_kernel4Args.numbered_sgpr, 102
	.set _Z10fwd_kernel4Args.num_named_barrier, 0
	.set _Z10fwd_kernel4Args.private_seg_size, 0
	.set _Z10fwd_kernel4Args.uses_vcc, 1
	.set _Z10fwd_kernel4Args.uses_flat_scratch, 0
	.set _Z10fwd_kernel4Args.has_dyn_sized_stack, 0
	.set _Z10fwd_kernel4Args.has_recursion, 0
	.set _Z10fwd_kernel4Args.has_indirect_call, 0

; __global__ void __launch_bounds__(NWAVES * 64, 2) fwd_kernel(Args args) {
;     __shared__ __attribute__((aligned(16))) unsigned char lds_raw[LDS_BYTES];
amdhsa.kernels:
  - .agpr_count:     0
    .args:
      - .offset:         0
        .size:           320
        .value_kind:     by_value
      - .offset:         320
        .size:           4
        .value_kind:     hidden_block_count_x
      - .offset:         324
        .size:           4
        .value_kind:     hidden_block_count_y
      - .offset:         328
        .size:           4
        .value_kind:     hidden_block_count_z
      - .offset:         332
        .size:           2
        .value_kind:     hidden_group_size_x
      - .offset:         334
        .size:           2
        .value_kind:     hidden_group_size_y
      - .offset:         336
        .size:           2
        .value_kind:     hidden_group_size_z
      - .offset:         338
        .size:           2
        .value_kind:     hidden_remainder_x
      - .offset:         340
        .size:           2
        .value_kind:     hidden_remainder_y
      - .offset:         342
        .size:           2
        .value_kind:     hidden_remainder_z
      - .offset:         360
        .size:           8
        .value_kind:     hidden_global_offset_x
      - .offset:         368
        .size:           8
        .value_kind:     hidden_global_offset_y
      - .offset:         376
        .size:           8
        .value_kind:     hidden_global_offset_z
      - .offset:         384
        .size:           2
        .value_kind:     hidden_grid_dims
    .group_segment_fixed_size: 147456
    .kernarg_segment_align: 8
    .kernarg_segment_size: 576
    .language:       OpenCL C
    .language_version:
      - 2
      - 0
    .max_flat_workgroup_size: 512
    .name:           _Z10fwd_kernel4Args
    .private_segment_fixed_size: 0
    .sgpr_count:     108
    .sgpr_spill_count: 60
    .symbol:         _Z10fwd_kernel4Args.kd
    .uniform_work_group_size: 1
    .uses_dynamic_stack: false
    .vgpr_count:     253
    .vgpr_spill_count: 0
    .wavefront_size: 64
